# SwiGLU GEMM epilogues: row-rms loads issued before the unit K-loop, epilogue no longer drains vmcnt(0) behind the next unit's tile prefetch
# speedup vs baseline: 1.0029x; 1.0029x over previous
.LBB0_102:
	v_lshl_add_u32 v248, s22, 8, v146
	v_lshlrev_b32_e32 v248, 2, v248
	global_load_dword v230, v248, s[80:81]
	global_load_dword v231, v248, s[80:81] offset:64
	global_load_dword v232, v248, s[80:81] offset:128
	global_load_dword v233, v248, s[80:81] offset:192
	global_load_dword v234, v248, s[80:81] offset:512
	global_load_dword v235, v248, s[80:81] offset:576
	global_load_dword v236, v248, s[80:81] offset:640
	global_load_dword v237, v248, s[80:81] offset:704
	s_ashr_i32 s17, s16, 31
	s_lshl_b64 s[0:1], s[16:17], 20
	s_add_u32 s18, s26, s0
	s_addc_u32 s19, s27, s1
	s_and_b64 s[0:1], s[6:7], exec
	s_cselect_b32 s17, s19, s25
	s_cselect_b32 s51, s18, s24
	s_ashr_i32 s15, s14, 31
	s_lshl_b64 s[0:1], s[14:15], 20
	s_add_u32 s20, s36, s0
	s_addc_u32 s21, s37, s1
	s_and_b64 s[0:1], s[6:7], exec
	s_cselect_b32 s15, s21, s29
	s_cselect_b32 s34, s20, s28
	s_add_u32 s24, s24, 0x80080
	s_addc_u32 s25, s25, 0
	s_add_u32 s35, s28, 0x100
	v_mov_b32_e32 v4, 0
	s_addc_u32 s52, s29, 0
	s_mov_b32 s61, -2
	v_mov_b32_e32 v5, v4
	v_mov_b32_e32 v6, v4
	v_mov_b32_e32 v7, v4
	v_mov_b32_e32 v12, v4
	v_mov_b32_e32 v13, v4
	v_mov_b32_e32 v14, v4
	v_mov_b32_e32 v15, v4
	v_mov_b32_e32 v20, v4
	v_mov_b32_e32 v21, v4
	v_mov_b32_e32 v22, v4
	v_mov_b32_e32 v23, v4
	v_mov_b32_e32 v28, v4
	v_mov_b32_e32 v29, v4
	v_mov_b32_e32 v30, v4
	v_mov_b32_e32 v31, v4
	v_mov_b32_e32 v36, v4
	v_mov_b32_e32 v37, v4
	v_mov_b32_e32 v38, v4
	v_mov_b32_e32 v39, v4
	v_mov_b32_e32 v44, v4
	v_mov_b32_e32 v45, v4
	v_mov_b32_e32 v46, v4
	v_mov_b32_e32 v47, v4
	v_mov_b32_e32 v52, v4
	v_mov_b32_e32 v53, v4
	v_mov_b32_e32 v54, v4
	v_mov_b32_e32 v55, v4
	v_mov_b32_e32 v60, v4
	v_mov_b32_e32 v61, v4
	v_mov_b32_e32 v62, v4
	v_mov_b32_e32 v63, v4
	v_mov_b32_e32 v0, v4
	v_mov_b32_e32 v1, v4
	v_mov_b32_e32 v2, v4
	v_mov_b32_e32 v3, v4
	v_mov_b32_e32 v8, v4
	v_mov_b32_e32 v9, v4
	v_mov_b32_e32 v10, v4
	v_mov_b32_e32 v11, v4
	v_mov_b32_e32 v16, v4
	v_mov_b32_e32 v17, v4
	v_mov_b32_e32 v18, v4
	v_mov_b32_e32 v19, v4
	v_mov_b32_e32 v24, v4
	v_mov_b32_e32 v25, v4
	v_mov_b32_e32 v26, v4
	v_mov_b32_e32 v27, v4
	v_mov_b32_e32 v32, v4
	v_mov_b32_e32 v33, v4
	v_mov_b32_e32 v34, v4
	v_mov_b32_e32 v35, v4
	v_mov_b32_e32 v40, v4
	v_mov_b32_e32 v41, v4
	v_mov_b32_e32 v42, v4
	v_mov_b32_e32 v43, v4
	v_mov_b32_e32 v48, v4
	v_mov_b32_e32 v49, v4
	v_mov_b32_e32 v50, v4
	v_mov_b32_e32 v51, v4
	v_mov_b32_e32 v56, v4
	v_mov_b32_e32 v57, v4
	v_mov_b32_e32 v58, v4
	v_mov_b32_e32 v59, v4
	v_mov_b32_e32 v68, v4
	v_mov_b32_e32 v69, v4
	v_mov_b32_e32 v70, v4
	v_mov_b32_e32 v71, v4
	v_mov_b32_e32 v76, v4
	v_mov_b32_e32 v77, v4
	v_mov_b32_e32 v78, v4
	v_mov_b32_e32 v79, v4
	v_mov_b32_e32 v84, v4
	v_mov_b32_e32 v85, v4
	v_mov_b32_e32 v86, v4
	v_mov_b32_e32 v87, v4
	v_mov_b32_e32 v92, v4
	v_mov_b32_e32 v93, v4
	v_mov_b32_e32 v94, v4
	v_mov_b32_e32 v95, v4
	v_mov_b32_e32 v100, v4
	v_mov_b32_e32 v101, v4
	v_mov_b32_e32 v102, v4
	v_mov_b32_e32 v103, v4
	v_mov_b32_e32 v104, v4
	v_mov_b32_e32 v105, v4
	v_mov_b32_e32 v106, v4
	v_mov_b32_e32 v107, v4
	v_mov_b32_e32 v112, v4
	v_mov_b32_e32 v113, v4
	v_mov_b32_e32 v114, v4
	v_mov_b32_e32 v115, v4
	v_mov_b32_e32 v120, v4
	v_mov_b32_e32 v121, v4
	v_mov_b32_e32 v122, v4
	v_mov_b32_e32 v123, v4
	v_mov_b32_e32 v64, v4
	v_mov_b32_e32 v65, v4
	v_mov_b32_e32 v66, v4
	v_mov_b32_e32 v67, v4
	v_mov_b32_e32 v72, v4
	v_mov_b32_e32 v73, v4
	v_mov_b32_e32 v74, v4
	v_mov_b32_e32 v75, v4
	v_mov_b32_e32 v80, v4
	v_mov_b32_e32 v81, v4
	v_mov_b32_e32 v82, v4
	v_mov_b32_e32 v83, v4
	v_mov_b32_e32 v88, v4
	v_mov_b32_e32 v89, v4
	v_mov_b32_e32 v90, v4
	v_mov_b32_e32 v91, v4
	v_mov_b32_e32 v96, v4
	v_mov_b32_e32 v97, v4
	v_mov_b32_e32 v98, v4
	v_mov_b32_e32 v99, v4
	v_mov_b32_e32 v108, v4
	v_mov_b32_e32 v109, v4
	v_mov_b32_e32 v110, v4
	v_mov_b32_e32 v111, v4
	v_mov_b32_e32 v116, v4
	v_mov_b32_e32 v117, v4
	v_mov_b32_e32 v118, v4
	v_mov_b32_e32 v119, v4
	v_mov_b32_e32 v124, v4
	v_mov_b32_e32 v125, v4
	v_mov_b32_e32 v126, v4
	v_mov_b32_e32 v127, v4

.LBB0_106:
	v_lshl_add_u32 v158, s22, 8, v146
	v_ashrrev_i32_e32 v159, 31, v158
	v_lshl_add_u64 v[138:139], v[158:159], 2, s[80:81]
	v_mov_b32_e32 v157, v230
	v_mov_b32_e32 v154, v234
	v_mov_b32_e32 v152, v235
	v_or_b32_e32 v144, 16, v158
	v_ashrrev_i32_e32 v145, 31, v144
	v_lshl_add_u64 v[140:141], v[144:145], 2, s[80:81]
	v_mov_b32_e32 v159, v231
	v_or_b32_e32 v142, 32, v158
	v_ashrrev_i32_e32 v143, 31, v142
	v_lshl_add_u64 v[140:141], v[142:143], 2, s[80:81]
	v_mov_b32_e32 v156, v232
	v_or_b32_e32 v140, 48, v158
	v_ashrrev_i32_e32 v141, 31, v140
	v_lshl_add_u64 v[150:151], v[140:141], 2, s[80:81]
	v_mov_b32_e32 v155, v233
	v_mov_b32_e32 v143, v237
	v_pk_mul_f32 v[120:121], v[124:125], v[120:121]
	v_mov_b32_e32 v150, v236
	v_pk_mul_f32 v[112:113], v[116:117], v[112:113]
	v_pk_mul_f32 v[114:115], v[118:119], v[114:115]
	v_lshl_or_b32 v138, s23, 7, v148
	v_pk_mul_f32 v[122:123], v[126:127], v[122:123]
	v_ashrrev_i32_e32 v139, 31, v138
	v_lshl_add_u64 v[138:139], v[138:139], 1, s[10:11]
	v_pk_mul_f32 v[104:105], v[108:109], v[104:105]
	v_pk_mul_f32 v[100:101], v[96:97], v[100:101]
	v_pk_mul_f32 v[102:103], v[98:99], v[102:103]
	v_pk_mul_f32 v[106:107], v[110:111], v[106:107]
	v_pk_mul_f32 v[92:93], v[88:89], v[92:93]
	v_pk_mul_f32 v[84:85], v[80:81], v[84:85]
	v_pk_mul_f32 v[94:95], v[90:91], v[94:95]
	v_pk_mul_f32 v[86:87], v[82:83], v[86:87]
	v_pk_mul_f32 v[76:77], v[72:73], v[76:77]
	v_pk_mul_f32 v[68:69], v[64:65], v[68:69]
	v_pk_mul_f32 v[78:79], v[74:75], v[78:79]
	v_pk_mul_f32 v[70:71], v[66:67], v[70:71]
	v_pk_mul_f32 v[60:61], v[56:57], v[60:61]
	v_pk_mul_f32 v[52:53], v[48:49], v[52:53]
	v_pk_mul_f32 v[62:63], v[58:59], v[62:63]
	v_pk_mul_f32 v[54:55], v[50:51], v[54:55]
	v_add_u32_e32 v153, 0x80, v158
	v_pk_mul_f32 v[44:45], v[40:41], v[44:45]
	v_pk_mul_f32 v[36:37], v[32:33], v[36:37]
	v_pk_mul_f32 v[46:47], v[42:43], v[46:47]
	v_pk_mul_f32 v[38:39], v[34:35], v[38:39]
	v_add_u32_e32 v151, 0x90, v158
	v_pk_mul_f32 v[28:29], v[24:25], v[28:29]
	v_pk_mul_f32 v[20:21], v[16:17], v[20:21]
	v_pk_mul_f32 v[30:31], v[26:27], v[30:31]
	v_pk_mul_f32 v[22:23], v[18:19], v[22:23]
	v_add_u32_e32 v145, 0xa0, v158
	v_pk_mul_f32 v[12:13], v[8:9], v[12:13]
	v_pk_mul_f32 v[4:5], v[0:1], v[4:5]
	v_pk_mul_f32 v[14:15], v[10:11], v[14:15]
	v_pk_mul_f32 v[6:7], v[2:3], v[6:7]
	v_add_u32_e32 v141, 0xb0, v158
	s_mov_b64 s[22:23], -1
	s_andn2_b64 vcc, exec, s[6:7]
	s_waitcnt vmcnt(8)
	v_fmamk_f32 v157, v157, 0x3a000000, v239
	v_rsq_f32_e32 v157, v157
	s_nop 0
	v_mul_f32_e32 v162, 0xbfb8aa3b, v157
	v_pk_mul_f32 v[124:125], v[124:125], v[162:163] op_sel_hi:[1,0]
	v_pk_mul_f32 v[116:117], v[116:117], v[162:163] op_sel_hi:[1,0]
	v_exp_f32_e32 v124, v124
	v_exp_f32_e32 v125, v125
	v_exp_f32_e32 v116, v116
	v_exp_f32_e32 v117, v117
	v_mul_f32_e32 v160, v157, v157
	v_pk_add_f32 v[124:125], v[124:125], 1.0 op_sel_hi:[1,0]
	v_pk_mul_f32 v[120:121], v[120:121], v[160:161] op_sel_hi:[1,0]
	v_pk_add_f32 v[116:117], v[116:117], 1.0 op_sel_hi:[1,0]
	v_rcp_f32_e32 v124, v124
	v_rcp_f32_e32 v125, v125
	v_rcp_f32_e32 v116, v116
	v_rcp_f32_e32 v117, v117
	v_pk_mul_f32 v[112:113], v[112:113], v[160:161] op_sel_hi:[1,0]
	v_pk_mul_f32 v[120:121], v[120:121], v[124:125]
	v_pk_mul_f32 v[124:125], v[126:127], v[162:163] op_sel_hi:[1,0]
	v_pk_mul_f32 v[116:117], v[112:113], v[116:117]
	v_pk_mul_f32 v[112:113], v[114:115], v[160:161] op_sel_hi:[1,0]
	v_pk_mul_f32 v[114:115], v[118:119], v[162:163] op_sel_hi:[1,0]
	v_exp_f32_e32 v124, v124
	v_exp_f32_e32 v125, v125
	v_exp_f32_e32 v114, v114
	v_exp_f32_e32 v115, v115
	v_pk_mul_f32 v[122:123], v[122:123], v[160:161] op_sel_hi:[1,0]
	v_pk_add_f32 v[124:125], v[124:125], 1.0 op_sel_hi:[1,0]
	v_pk_add_f32 v[114:115], v[114:115], 1.0 op_sel_hi:[1,0]
	v_rcp_f32_e32 v124, v124
	v_rcp_f32_e32 v125, v125
	v_rcp_f32_e32 v114, v114
	v_rcp_f32_e32 v115, v115
	v_pk_mul_f32 v[122:123], v[122:123], v[124:125]
	v_pk_mul_f32 v[118:119], v[112:113], v[114:115]
	v_cvt_pk_bf16_f32 v112, v120, v121
	v_cvt_pk_bf16_f32 v113, v122, v123
	v_cvt_pk_bf16_f32 v114, v116, v117
	v_cvt_pk_bf16_f32 v115, v118, v119
	v_mad_i64_i32 v[116:117], s[0:1], v158, s95, v[138:139]
	global_store_dwordx4 v[116:117], v[112:115], off
	s_nop 1
	v_fmamk_f32 v112, v159, 0x3a000000, v239
	v_rsq_f32_e32 v112, v112
	s_nop 0
	v_mul_f32_e32 v114, v112, v112
	v_mul_f32_e32 v112, 0xbfb8aa3b, v112
	v_pk_mul_f32 v[108:109], v[108:109], v[112:113] op_sel_hi:[1,0]
	v_pk_mul_f32 v[104:105], v[104:105], v[114:115] op_sel_hi:[1,0]
	v_exp_f32_e32 v108, v108
	v_exp_f32_e32 v109, v109
	v_pk_mul_f32 v[96:97], v[96:97], v[112:113] op_sel_hi:[1,0]
	v_pk_mul_f32 v[98:99], v[98:99], v[112:113] op_sel_hi:[1,0]
	v_exp_f32_e32 v96, v96
	v_pk_add_f32 v[108:109], v[108:109], 1.0 op_sel_hi:[1,0]
	v_exp_f32_e32 v97, v97
	v_rcp_f32_e32 v108, v108
	v_rcp_f32_e32 v109, v109
	v_exp_f32_e32 v98, v98
	v_exp_f32_e32 v99, v99
	v_pk_add_f32 v[96:97], v[96:97], 1.0 op_sel_hi:[1,0]
	v_pk_mul_f32 v[104:105], v[104:105], v[108:109]
	v_pk_mul_f32 v[108:109], v[110:111], v[112:113] op_sel_hi:[1,0]
	v_rcp_f32_e32 v96, v96
	v_exp_f32_e32 v108, v108
	v_exp_f32_e32 v109, v109
	v_rcp_f32_e32 v97, v97
	v_pk_add_f32 v[98:99], v[98:99], 1.0 op_sel_hi:[1,0]
	v_pk_mul_f32 v[100:101], v[100:101], v[114:115] op_sel_hi:[1,0]
	v_pk_add_f32 v[108:109], v[108:109], 1.0 op_sel_hi:[1,0]
	v_rcp_f32_e32 v98, v98
	v_rcp_f32_e32 v108, v108
	v_rcp_f32_e32 v109, v109
	v_rcp_f32_e32 v99, v99
	v_pk_mul_f32 v[106:107], v[106:107], v[114:115] op_sel_hi:[1,0]
	v_pk_mul_f32 v[100:101], v[100:101], v[96:97]
	v_pk_mul_f32 v[96:97], v[102:103], v[114:115] op_sel_hi:[1,0]
	v_pk_mul_f32 v[106:107], v[106:107], v[108:109]
	v_pk_mul_f32 v[102:103], v[96:97], v[98:99]
	v_cvt_pk_bf16_f32 v96, v104, v105
	v_cvt_pk_bf16_f32 v97, v106, v107
	v_cvt_pk_bf16_f32 v98, v100, v101
	v_cvt_pk_bf16_f32 v99, v102, v103
	v_mad_i64_i32 v[100:101], s[0:1], v144, s95, v[138:139]
	global_store_dwordx4 v[100:101], v[96:99], off
	s_nop 1
	v_fmamk_f32 v96, v156, 0x3a000000, v239
	v_rsq_f32_e32 v97, v96
	s_nop 0
	v_mul_f32_e32 v98, 0xbfb8aa3b, v97
	v_pk_mul_f32 v[88:89], v[88:89], v[98:99] op_sel_hi:[1,0]
	v_pk_mul_f32 v[80:81], v[80:81], v[98:99] op_sel_hi:[1,0]
	v_exp_f32_e32 v88, v88
	v_exp_f32_e32 v89, v89
	v_pk_mul_f32 v[90:91], v[90:91], v[98:99] op_sel_hi:[1,0]
	v_exp_f32_e32 v80, v80
	v_exp_f32_e32 v81, v81
	v_pk_mul_f32 v[82:83], v[82:83], v[98:99] op_sel_hi:[1,0]
	v_exp_f32_e32 v90, v90
	v_exp_f32_e32 v91, v91
	v_exp_f32_e32 v82, v82
	v_exp_f32_e32 v83, v83
	v_pk_add_f32 v[88:89], v[88:89], 1.0 op_sel_hi:[1,0]
	v_pk_add_f32 v[80:81], v[80:81], 1.0 op_sel_hi:[1,0]
	v_rcp_f32_e32 v88, v88
	v_rcp_f32_e32 v89, v89
	v_pk_add_f32 v[90:91], v[90:91], 1.0 op_sel_hi:[1,0]
	v_rcp_f32_e32 v80, v80
	v_rcp_f32_e32 v81, v81
	v_pk_add_f32 v[82:83], v[82:83], 1.0 op_sel_hi:[1,0]
	v_rcp_f32_e32 v90, v90
	v_rcp_f32_e32 v91, v91
	v_rcp_f32_e32 v82, v82
	v_rcp_f32_e32 v83, v83
	v_mul_f32_e32 v96, v97, v97
	v_pk_mul_f32 v[92:93], v[92:93], v[96:97] op_sel_hi:[1,0]
	v_pk_mul_f32 v[84:85], v[84:85], v[96:97] op_sel_hi:[1,0]
	v_pk_mul_f32 v[88:89], v[92:93], v[88:89]
	v_pk_mul_f32 v[92:93], v[94:95], v[96:97] op_sel_hi:[1,0]
	v_pk_mul_f32 v[84:85], v[84:85], v[80:81]
	v_pk_mul_f32 v[80:81], v[86:87], v[96:97] op_sel_hi:[1,0]
	v_pk_mul_f32 v[90:91], v[92:93], v[90:91]
	v_pk_mul_f32 v[86:87], v[80:81], v[82:83]
	v_cvt_pk_bf16_f32 v80, v88, v89
	v_cvt_pk_bf16_f32 v81, v90, v91
	v_cvt_pk_bf16_f32 v82, v84, v85
	v_cvt_pk_bf16_f32 v83, v86, v87
	v_mad_i64_i32 v[84:85], s[0:1], v142, s95, v[138:139]
	global_store_dwordx4 v[84:85], v[80:83], off
	s_nop 1
	v_fmamk_f32 v80, v155, 0x3a000000, v239
	v_rsq_f32_e32 v81, v80
	s_nop 0
	v_mul_f32_e32 v82, 0xbfb8aa3b, v81
	v_pk_mul_f32 v[72:73], v[72:73], v[82:83] op_sel_hi:[1,0]
	v_pk_mul_f32 v[64:65], v[64:65], v[82:83] op_sel_hi:[1,0]
	v_exp_f32_e32 v72, v72
	v_exp_f32_e32 v73, v73
	v_pk_mul_f32 v[74:75], v[74:75], v[82:83] op_sel_hi:[1,0]
	v_exp_f32_e32 v64, v64
	v_exp_f32_e32 v65, v65
	v_pk_mul_f32 v[66:67], v[66:67], v[82:83] op_sel_hi:[1,0]
	v_exp_f32_e32 v74, v74
	v_exp_f32_e32 v75, v75
	v_exp_f32_e32 v66, v66
	v_exp_f32_e32 v67, v67
	v_pk_add_f32 v[72:73], v[72:73], 1.0 op_sel_hi:[1,0]
	v_pk_add_f32 v[64:65], v[64:65], 1.0 op_sel_hi:[1,0]
	v_rcp_f32_e32 v72, v72
	v_rcp_f32_e32 v73, v73
	v_pk_add_f32 v[74:75], v[74:75], 1.0 op_sel_hi:[1,0]
	v_rcp_f32_e32 v64, v64
	v_rcp_f32_e32 v65, v65
	v_pk_add_f32 v[66:67], v[66:67], 1.0 op_sel_hi:[1,0]
	v_rcp_f32_e32 v74, v74
	v_rcp_f32_e32 v75, v75
	v_rcp_f32_e32 v66, v66
	v_rcp_f32_e32 v67, v67
	v_mul_f32_e32 v80, v81, v81
	v_pk_mul_f32 v[76:77], v[76:77], v[80:81] op_sel_hi:[1,0]
	v_pk_mul_f32 v[68:69], v[68:69], v[80:81] op_sel_hi:[1,0]
	v_pk_mul_f32 v[72:73], v[76:77], v[72:73]
	v_pk_mul_f32 v[76:77], v[78:79], v[80:81] op_sel_hi:[1,0]
	v_pk_mul_f32 v[68:69], v[68:69], v[64:65]
	v_pk_mul_f32 v[64:65], v[70:71], v[80:81] op_sel_hi:[1,0]
	v_pk_mul_f32 v[74:75], v[76:77], v[74:75]
	v_pk_mul_f32 v[70:71], v[64:65], v[66:67]
	v_cvt_pk_bf16_f32 v64, v72, v73
	v_cvt_pk_bf16_f32 v65, v74, v75
	v_cvt_pk_bf16_f32 v66, v68, v69
	v_cvt_pk_bf16_f32 v67, v70, v71
	v_mad_i64_i32 v[68:69], s[0:1], v140, s95, v[138:139]
	global_store_dwordx4 v[68:69], v[64:67], off
	s_nop 1
	v_fmamk_f32 v64, v154, 0x3a000000, v239
	v_rsq_f32_e32 v65, v64
	s_nop 0
	v_mul_f32_e32 v66, 0xbfb8aa3b, v65
	v_pk_mul_f32 v[56:57], v[56:57], v[66:67] op_sel_hi:[1,0]
	v_pk_mul_f32 v[48:49], v[48:49], v[66:67] op_sel_hi:[1,0]
	v_exp_f32_e32 v56, v56
	v_exp_f32_e32 v57, v57
	v_pk_mul_f32 v[58:59], v[58:59], v[66:67] op_sel_hi:[1,0]
	v_exp_f32_e32 v48, v48
	v_exp_f32_e32 v49, v49
	v_pk_mul_f32 v[50:51], v[50:51], v[66:67] op_sel_hi:[1,0]
	v_exp_f32_e32 v58, v58
	v_exp_f32_e32 v59, v59
	v_exp_f32_e32 v50, v50
	v_exp_f32_e32 v51, v51
	v_pk_add_f32 v[56:57], v[56:57], 1.0 op_sel_hi:[1,0]
	v_pk_add_f32 v[48:49], v[48:49], 1.0 op_sel_hi:[1,0]
	v_rcp_f32_e32 v56, v56
	v_rcp_f32_e32 v57, v57
	v_pk_add_f32 v[58:59], v[58:59], 1.0 op_sel_hi:[1,0]
	v_rcp_f32_e32 v48, v48
	v_rcp_f32_e32 v49, v49
	v_pk_add_f32 v[50:51], v[50:51], 1.0 op_sel_hi:[1,0]
	v_rcp_f32_e32 v58, v58
	v_rcp_f32_e32 v59, v59
	v_rcp_f32_e32 v50, v50
	v_rcp_f32_e32 v51, v51
	v_mul_f32_e32 v64, v65, v65
	v_pk_mul_f32 v[60:61], v[60:61], v[64:65] op_sel_hi:[1,0]
	v_pk_mul_f32 v[52:53], v[52:53], v[64:65] op_sel_hi:[1,0]
	v_pk_mul_f32 v[56:57], v[60:61], v[56:57]
	v_pk_mul_f32 v[60:61], v[62:63], v[64:65] op_sel_hi:[1,0]
	v_pk_mul_f32 v[52:53], v[52:53], v[48:49]
	v_pk_mul_f32 v[48:49], v[54:55], v[64:65] op_sel_hi:[1,0]
	v_pk_mul_f32 v[58:59], v[60:61], v[58:59]
	v_pk_mul_f32 v[54:55], v[48:49], v[50:51]
	v_cvt_pk_bf16_f32 v48, v56, v57
	v_cvt_pk_bf16_f32 v49, v58, v59
	v_cvt_pk_bf16_f32 v50, v52, v53
	v_cvt_pk_bf16_f32 v51, v54, v55
	v_mad_i64_i32 v[52:53], s[0:1], v153, s95, v[138:139]
	global_store_dwordx4 v[52:53], v[48:51], off
	s_nop 1
	v_fmamk_f32 v48, v152, 0x3a000000, v239
	v_rsq_f32_e32 v49, v48
	s_nop 0
	v_mul_f32_e32 v50, 0xbfb8aa3b, v49
	v_pk_mul_f32 v[40:41], v[40:41], v[50:51] op_sel_hi:[1,0]
	v_pk_mul_f32 v[32:33], v[32:33], v[50:51] op_sel_hi:[1,0]
	v_exp_f32_e32 v40, v40
	v_exp_f32_e32 v41, v41
	v_pk_mul_f32 v[42:43], v[42:43], v[50:51] op_sel_hi:[1,0]
	v_exp_f32_e32 v32, v32
	v_exp_f32_e32 v33, v33
	v_pk_mul_f32 v[34:35], v[34:35], v[50:51] op_sel_hi:[1,0]
	v_exp_f32_e32 v42, v42
	v_exp_f32_e32 v43, v43
	v_exp_f32_e32 v34, v34
	v_exp_f32_e32 v35, v35
	v_pk_add_f32 v[40:41], v[40:41], 1.0 op_sel_hi:[1,0]
	v_pk_add_f32 v[32:33], v[32:33], 1.0 op_sel_hi:[1,0]
	v_rcp_f32_e32 v40, v40
	v_rcp_f32_e32 v41, v41
	v_pk_add_f32 v[42:43], v[42:43], 1.0 op_sel_hi:[1,0]
	v_rcp_f32_e32 v32, v32
	v_rcp_f32_e32 v33, v33
	v_pk_add_f32 v[34:35], v[34:35], 1.0 op_sel_hi:[1,0]
	v_rcp_f32_e32 v42, v42
	v_rcp_f32_e32 v43, v43
	v_rcp_f32_e32 v34, v34
	v_rcp_f32_e32 v35, v35
	v_mul_f32_e32 v48, v49, v49
	v_pk_mul_f32 v[44:45], v[44:45], v[48:49] op_sel_hi:[1,0]
	v_pk_mul_f32 v[36:37], v[36:37], v[48:49] op_sel_hi:[1,0]
	v_pk_mul_f32 v[40:41], v[44:45], v[40:41]
	v_pk_mul_f32 v[44:45], v[46:47], v[48:49] op_sel_hi:[1,0]
	v_pk_mul_f32 v[36:37], v[36:37], v[32:33]
	v_pk_mul_f32 v[32:33], v[38:39], v[48:49] op_sel_hi:[1,0]
	v_pk_mul_f32 v[42:43], v[44:45], v[42:43]
	v_pk_mul_f32 v[38:39], v[32:33], v[34:35]
	v_cvt_pk_bf16_f32 v32, v40, v41
	v_cvt_pk_bf16_f32 v33, v42, v43
	v_cvt_pk_bf16_f32 v34, v36, v37
	v_cvt_pk_bf16_f32 v35, v38, v39
	v_mad_i64_i32 v[36:37], s[0:1], v151, s95, v[138:139]
	global_store_dwordx4 v[36:37], v[32:35], off
	s_nop 1
	v_fmamk_f32 v32, v150, 0x3a000000, v239
	v_rsq_f32_e32 v33, v32
	s_nop 0
	v_mul_f32_e32 v34, 0xbfb8aa3b, v33
	v_pk_mul_f32 v[24:25], v[24:25], v[34:35] op_sel_hi:[1,0]
	v_pk_mul_f32 v[16:17], v[16:17], v[34:35] op_sel_hi:[1,0]
	v_exp_f32_e32 v24, v24
	v_exp_f32_e32 v25, v25
	v_pk_mul_f32 v[26:27], v[26:27], v[34:35] op_sel_hi:[1,0]
	v_exp_f32_e32 v16, v16
	v_exp_f32_e32 v17, v17
	v_pk_mul_f32 v[18:19], v[18:19], v[34:35] op_sel_hi:[1,0]
	v_exp_f32_e32 v26, v26
	v_exp_f32_e32 v27, v27
	v_exp_f32_e32 v18, v18
	v_exp_f32_e32 v19, v19
	v_pk_add_f32 v[24:25], v[24:25], 1.0 op_sel_hi:[1,0]
	v_pk_add_f32 v[16:17], v[16:17], 1.0 op_sel_hi:[1,0]
	v_rcp_f32_e32 v24, v24
	v_rcp_f32_e32 v25, v25
	v_pk_add_f32 v[26:27], v[26:27], 1.0 op_sel_hi:[1,0]
	v_rcp_f32_e32 v16, v16
	v_rcp_f32_e32 v17, v17
	v_pk_add_f32 v[18:19], v[18:19], 1.0 op_sel_hi:[1,0]
	v_rcp_f32_e32 v26, v26
	v_rcp_f32_e32 v27, v27
	v_rcp_f32_e32 v18, v18
	v_rcp_f32_e32 v19, v19
	v_mul_f32_e32 v32, v33, v33
	v_pk_mul_f32 v[28:29], v[28:29], v[32:33] op_sel_hi:[1,0]
	v_pk_mul_f32 v[20:21], v[20:21], v[32:33] op_sel_hi:[1,0]
	v_pk_mul_f32 v[24:25], v[28:29], v[24:25]
	v_pk_mul_f32 v[28:29], v[30:31], v[32:33] op_sel_hi:[1,0]
	v_pk_mul_f32 v[20:21], v[20:21], v[16:17]
	v_pk_mul_f32 v[16:17], v[22:23], v[32:33] op_sel_hi:[1,0]
	v_pk_mul_f32 v[26:27], v[28:29], v[26:27]
	v_pk_mul_f32 v[22:23], v[16:17], v[18:19]
	v_cvt_pk_bf16_f32 v16, v24, v25
	v_cvt_pk_bf16_f32 v17, v26, v27
	v_cvt_pk_bf16_f32 v18, v20, v21
	v_cvt_pk_bf16_f32 v19, v22, v23
	v_mad_i64_i32 v[20:21], s[0:1], v145, s95, v[138:139]
	global_store_dwordx4 v[20:21], v[16:19], off
	s_nop 1
	v_fmamk_f32 v16, v143, 0x3a000000, v239
	v_rsq_f32_e32 v17, v16
	s_nop 0
	v_mul_f32_e32 v18, 0xbfb8aa3b, v17
	v_pk_mul_f32 v[8:9], v[8:9], v[18:19] op_sel_hi:[1,0]
	v_pk_mul_f32 v[0:1], v[0:1], v[18:19] op_sel_hi:[1,0]
	v_exp_f32_e32 v8, v8
	v_exp_f32_e32 v9, v9
	v_pk_mul_f32 v[10:11], v[10:11], v[18:19] op_sel_hi:[1,0]
	v_exp_f32_e32 v0, v0
	v_exp_f32_e32 v1, v1
	v_pk_mul_f32 v[2:3], v[2:3], v[18:19] op_sel_hi:[1,0]
	v_exp_f32_e32 v10, v10
	v_exp_f32_e32 v11, v11
	v_exp_f32_e32 v2, v2
	v_exp_f32_e32 v3, v3
	v_pk_add_f32 v[8:9], v[8:9], 1.0 op_sel_hi:[1,0]
	v_pk_add_f32 v[0:1], v[0:1], 1.0 op_sel_hi:[1,0]
	v_rcp_f32_e32 v8, v8
	v_rcp_f32_e32 v9, v9
	v_pk_add_f32 v[10:11], v[10:11], 1.0 op_sel_hi:[1,0]
	v_rcp_f32_e32 v0, v0
	v_rcp_f32_e32 v1, v1
	v_pk_add_f32 v[2:3], v[2:3], 1.0 op_sel_hi:[1,0]
	v_rcp_f32_e32 v10, v10
	v_rcp_f32_e32 v11, v11
	v_rcp_f32_e32 v2, v2
	v_rcp_f32_e32 v3, v3
	v_mul_f32_e32 v16, v17, v17
	v_pk_mul_f32 v[12:13], v[12:13], v[16:17] op_sel_hi:[1,0]
	v_pk_mul_f32 v[4:5], v[4:5], v[16:17] op_sel_hi:[1,0]
	v_pk_mul_f32 v[8:9], v[12:13], v[8:9]
	v_pk_mul_f32 v[12:13], v[14:15], v[16:17] op_sel_hi:[1,0]
	v_pk_mul_f32 v[4:5], v[4:5], v[0:1]
	v_pk_mul_f32 v[0:1], v[6:7], v[16:17] op_sel_hi:[1,0]
	v_pk_mul_f32 v[10:11], v[12:13], v[10:11]
	v_pk_mul_f32 v[6:7], v[0:1], v[2:3]
	v_cvt_pk_bf16_f32 v0, v8, v9
	v_cvt_pk_bf16_f32 v1, v10, v11
	v_cvt_pk_bf16_f32 v2, v4, v5
	v_cvt_pk_bf16_f32 v3, v6, v7
	v_mad_i64_i32 v[4:5], s[0:1], v141, s95, v[138:139]
	global_store_dwordx4 v[4:5], v[0:3], off
	s_cbranch_vccnz .LBB0_99
	s_andn2_b64 vcc, exec, s[8:9]
	s_cbranch_vccnz .LBB0_98
	s_barrier
	s_branch .LBB0_98

.LBB0_527:
	v_lshl_add_u32 v248, s28, 8, v146
	v_lshlrev_b32_e32 v248, 2, v248
	global_load_dword v230, v248, s[72:73]
	global_load_dword v231, v248, s[72:73] offset:64
	global_load_dword v232, v248, s[72:73] offset:128
	global_load_dword v233, v248, s[72:73] offset:192
	global_load_dword v234, v248, s[72:73] offset:512
	global_load_dword v235, v248, s[72:73] offset:576
	global_load_dword v236, v248, s[72:73] offset:640
	global_load_dword v237, v248, s[72:73] offset:704
	s_ashr_i32 s17, s16, 31
	s_lshl_b64 s[0:1], s[16:17], 20
	s_add_u32 s18, s26, s0
	s_addc_u32 s19, s27, s1
	s_and_b64 s[0:1], s[6:7], exec
	s_cselect_b32 s17, s19, s31
	s_cselect_b32 s51, s18, s30
	s_ashr_i32 s15, s14, 31
	s_lshl_b64 s[0:1], s[14:15], 20
	s_add_u32 s20, s70, s0
	s_addc_u32 s21, s71, s1
	s_and_b64 s[0:1], s[6:7], exec
	s_cselect_b32 s15, s21, s37
	s_cselect_b32 s34, s20, s36
	s_add_u32 s30, s30, 0x80080
	s_addc_u32 s31, s31, 0
	s_add_u32 s35, s36, 0x100
	v_mov_b32_e32 v4, 0
	s_addc_u32 s52, s37, 0
	s_mov_b32 s61, -2
	v_mov_b32_e32 v5, v4
	v_mov_b32_e32 v6, v4
	v_mov_b32_e32 v7, v4
	v_mov_b32_e32 v12, v4
	v_mov_b32_e32 v13, v4
	v_mov_b32_e32 v14, v4
	v_mov_b32_e32 v15, v4
	v_mov_b32_e32 v20, v4
	v_mov_b32_e32 v21, v4
	v_mov_b32_e32 v22, v4
	v_mov_b32_e32 v23, v4
	v_mov_b32_e32 v28, v4
	v_mov_b32_e32 v29, v4
	v_mov_b32_e32 v30, v4
	v_mov_b32_e32 v31, v4
	v_mov_b32_e32 v36, v4
	v_mov_b32_e32 v37, v4
	v_mov_b32_e32 v38, v4
	v_mov_b32_e32 v39, v4
	v_mov_b32_e32 v44, v4
	v_mov_b32_e32 v45, v4
	v_mov_b32_e32 v46, v4
	v_mov_b32_e32 v47, v4
	v_mov_b32_e32 v52, v4
	v_mov_b32_e32 v53, v4
	v_mov_b32_e32 v54, v4
	v_mov_b32_e32 v55, v4
	v_mov_b32_e32 v60, v4
	v_mov_b32_e32 v61, v4
	v_mov_b32_e32 v62, v4
	v_mov_b32_e32 v63, v4
	v_mov_b32_e32 v0, v4
	v_mov_b32_e32 v1, v4
	v_mov_b32_e32 v2, v4
	v_mov_b32_e32 v3, v4
	v_mov_b32_e32 v8, v4
	v_mov_b32_e32 v9, v4
	v_mov_b32_e32 v10, v4
	v_mov_b32_e32 v11, v4
	v_mov_b32_e32 v16, v4
	v_mov_b32_e32 v17, v4
	v_mov_b32_e32 v18, v4
	v_mov_b32_e32 v19, v4
	v_mov_b32_e32 v24, v4
	v_mov_b32_e32 v25, v4
	v_mov_b32_e32 v26, v4
	v_mov_b32_e32 v27, v4
	v_mov_b32_e32 v32, v4
	v_mov_b32_e32 v33, v4
	v_mov_b32_e32 v34, v4
	v_mov_b32_e32 v35, v4
	v_mov_b32_e32 v40, v4
	v_mov_b32_e32 v41, v4
	v_mov_b32_e32 v42, v4
	v_mov_b32_e32 v43, v4
	v_mov_b32_e32 v48, v4
	v_mov_b32_e32 v49, v4
	v_mov_b32_e32 v50, v4
	v_mov_b32_e32 v51, v4
	v_mov_b32_e32 v56, v4
	v_mov_b32_e32 v57, v4
	v_mov_b32_e32 v58, v4
	v_mov_b32_e32 v59, v4
	v_mov_b32_e32 v68, v4
	v_mov_b32_e32 v69, v4
	v_mov_b32_e32 v70, v4
	v_mov_b32_e32 v71, v4
	v_mov_b32_e32 v76, v4
	v_mov_b32_e32 v77, v4
	v_mov_b32_e32 v78, v4
	v_mov_b32_e32 v79, v4
	v_mov_b32_e32 v84, v4
	v_mov_b32_e32 v85, v4
	v_mov_b32_e32 v86, v4
	v_mov_b32_e32 v87, v4
	v_mov_b32_e32 v92, v4
	v_mov_b32_e32 v93, v4
	v_mov_b32_e32 v94, v4
	v_mov_b32_e32 v95, v4
	v_mov_b32_e32 v100, v4
	v_mov_b32_e32 v101, v4
	v_mov_b32_e32 v102, v4
	v_mov_b32_e32 v103, v4
	v_mov_b32_e32 v104, v4
	v_mov_b32_e32 v105, v4
	v_mov_b32_e32 v106, v4
	v_mov_b32_e32 v107, v4
	v_mov_b32_e32 v112, v4
	v_mov_b32_e32 v113, v4
	v_mov_b32_e32 v114, v4
	v_mov_b32_e32 v115, v4
	v_mov_b32_e32 v120, v4
	v_mov_b32_e32 v121, v4
	v_mov_b32_e32 v122, v4
	v_mov_b32_e32 v123, v4
	v_mov_b32_e32 v64, v4
	v_mov_b32_e32 v65, v4
	v_mov_b32_e32 v66, v4
	v_mov_b32_e32 v67, v4
	v_mov_b32_e32 v72, v4
	v_mov_b32_e32 v73, v4
	v_mov_b32_e32 v74, v4
	v_mov_b32_e32 v75, v4
	v_mov_b32_e32 v80, v4
	v_mov_b32_e32 v81, v4
	v_mov_b32_e32 v82, v4
	v_mov_b32_e32 v83, v4
	v_mov_b32_e32 v88, v4
	v_mov_b32_e32 v89, v4
	v_mov_b32_e32 v90, v4
	v_mov_b32_e32 v91, v4
	v_mov_b32_e32 v96, v4
	v_mov_b32_e32 v97, v4
	v_mov_b32_e32 v98, v4
	v_mov_b32_e32 v99, v4
	v_mov_b32_e32 v108, v4
	v_mov_b32_e32 v109, v4
	v_mov_b32_e32 v110, v4
	v_mov_b32_e32 v111, v4
	v_mov_b32_e32 v116, v4
	v_mov_b32_e32 v117, v4
	v_mov_b32_e32 v118, v4
	v_mov_b32_e32 v119, v4
	v_mov_b32_e32 v124, v4
	v_mov_b32_e32 v125, v4
	v_mov_b32_e32 v126, v4
	v_mov_b32_e32 v127, v4

.LBB0_531:
	v_lshl_add_u32 v158, s28, 8, v146
	v_ashrrev_i32_e32 v159, 31, v158
	v_lshl_add_u64 v[138:139], v[158:159], 2, s[72:73]
	v_mov_b32_e32 v157, v230
	v_mov_b32_e32 v154, v234
	v_mov_b32_e32 v152, v235
	v_or_b32_e32 v144, 16, v158
	v_ashrrev_i32_e32 v145, 31, v144
	v_lshl_add_u64 v[140:141], v[144:145], 2, s[72:73]
	v_mov_b32_e32 v159, v231
	v_or_b32_e32 v142, 32, v158
	v_ashrrev_i32_e32 v143, 31, v142
	v_lshl_add_u64 v[140:141], v[142:143], 2, s[72:73]
	v_mov_b32_e32 v156, v232
	v_or_b32_e32 v140, 48, v158
	v_ashrrev_i32_e32 v141, 31, v140
	v_lshl_add_u64 v[150:151], v[140:141], 2, s[72:73]
	v_mov_b32_e32 v155, v233
	v_mov_b32_e32 v143, v237
	v_pk_mul_f32 v[120:121], v[124:125], v[120:121]
	v_mov_b32_e32 v150, v236
	v_pk_mul_f32 v[112:113], v[116:117], v[112:113]
	v_pk_mul_f32 v[114:115], v[118:119], v[114:115]
	v_lshl_or_b32 v138, s29, 7, v148
	v_pk_mul_f32 v[122:123], v[126:127], v[122:123]
	v_ashrrev_i32_e32 v139, 31, v138
	v_lshl_add_u64 v[138:139], v[138:139], 1, s[10:11]
	v_pk_mul_f32 v[104:105], v[108:109], v[104:105]
	v_pk_mul_f32 v[100:101], v[96:97], v[100:101]
	v_pk_mul_f32 v[102:103], v[98:99], v[102:103]
	v_pk_mul_f32 v[106:107], v[110:111], v[106:107]
	v_pk_mul_f32 v[92:93], v[88:89], v[92:93]
	v_pk_mul_f32 v[84:85], v[80:81], v[84:85]
	v_pk_mul_f32 v[94:95], v[90:91], v[94:95]
	v_pk_mul_f32 v[86:87], v[82:83], v[86:87]
	v_pk_mul_f32 v[76:77], v[72:73], v[76:77]
	v_pk_mul_f32 v[68:69], v[64:65], v[68:69]
	v_pk_mul_f32 v[78:79], v[74:75], v[78:79]
	v_pk_mul_f32 v[70:71], v[66:67], v[70:71]
	v_pk_mul_f32 v[60:61], v[56:57], v[60:61]
	v_pk_mul_f32 v[52:53], v[48:49], v[52:53]
	v_pk_mul_f32 v[62:63], v[58:59], v[62:63]
	v_pk_mul_f32 v[54:55], v[50:51], v[54:55]
	v_add_u32_e32 v153, 0x80, v158
	v_pk_mul_f32 v[44:45], v[40:41], v[44:45]
	v_pk_mul_f32 v[36:37], v[32:33], v[36:37]
	v_pk_mul_f32 v[46:47], v[42:43], v[46:47]
	v_pk_mul_f32 v[38:39], v[34:35], v[38:39]
	v_add_u32_e32 v151, 0x90, v158
	v_pk_mul_f32 v[28:29], v[24:25], v[28:29]
	v_pk_mul_f32 v[20:21], v[16:17], v[20:21]
	v_pk_mul_f32 v[30:31], v[26:27], v[30:31]
	v_pk_mul_f32 v[22:23], v[18:19], v[22:23]
	v_add_u32_e32 v145, 0xa0, v158
	v_pk_mul_f32 v[12:13], v[8:9], v[12:13]
	v_pk_mul_f32 v[4:5], v[0:1], v[4:5]
	v_pk_mul_f32 v[14:15], v[10:11], v[14:15]
	v_pk_mul_f32 v[6:7], v[2:3], v[6:7]
	v_add_u32_e32 v141, 0xb0, v158
	s_mov_b64 s[28:29], -1
	s_andn2_b64 vcc, exec, s[6:7]
	s_waitcnt vmcnt(8)
	v_fmamk_f32 v157, v157, 0x3a000000, v239
	v_rsq_f32_e32 v157, v157
	s_nop 0
	v_mul_f32_e32 v162, 0xbfb8aa3b, v157
	v_pk_mul_f32 v[124:125], v[124:125], v[162:163] op_sel_hi:[1,0]
	v_pk_mul_f32 v[116:117], v[116:117], v[162:163] op_sel_hi:[1,0]
	v_exp_f32_e32 v124, v124
	v_exp_f32_e32 v125, v125
	v_exp_f32_e32 v116, v116
	v_exp_f32_e32 v117, v117
	v_mul_f32_e32 v160, v157, v157
	v_pk_add_f32 v[124:125], v[124:125], 1.0 op_sel_hi:[1,0]
	v_pk_mul_f32 v[120:121], v[120:121], v[160:161] op_sel_hi:[1,0]
	v_pk_add_f32 v[116:117], v[116:117], 1.0 op_sel_hi:[1,0]
	v_rcp_f32_e32 v124, v124
	v_rcp_f32_e32 v125, v125
	v_rcp_f32_e32 v116, v116
	v_rcp_f32_e32 v117, v117
	v_pk_mul_f32 v[112:113], v[112:113], v[160:161] op_sel_hi:[1,0]
	v_pk_mul_f32 v[120:121], v[120:121], v[124:125]
	v_pk_mul_f32 v[124:125], v[126:127], v[162:163] op_sel_hi:[1,0]
	v_pk_mul_f32 v[116:117], v[112:113], v[116:117]
	v_pk_mul_f32 v[112:113], v[114:115], v[160:161] op_sel_hi:[1,0]
	v_pk_mul_f32 v[114:115], v[118:119], v[162:163] op_sel_hi:[1,0]
	v_exp_f32_e32 v124, v124
	v_exp_f32_e32 v125, v125
	v_exp_f32_e32 v114, v114
	v_exp_f32_e32 v115, v115
	v_pk_mul_f32 v[122:123], v[122:123], v[160:161] op_sel_hi:[1,0]
	v_pk_add_f32 v[124:125], v[124:125], 1.0 op_sel_hi:[1,0]
	v_pk_add_f32 v[114:115], v[114:115], 1.0 op_sel_hi:[1,0]
	v_rcp_f32_e32 v124, v124
	v_rcp_f32_e32 v125, v125
	v_rcp_f32_e32 v114, v114
	v_rcp_f32_e32 v115, v115
	v_pk_mul_f32 v[122:123], v[122:123], v[124:125]
	v_pk_mul_f32 v[118:119], v[112:113], v[114:115]
	v_cvt_pk_bf16_f32 v112, v120, v121
	v_cvt_pk_bf16_f32 v113, v122, v123
	v_cvt_pk_bf16_f32 v114, v116, v117
	v_cvt_pk_bf16_f32 v115, v118, v119
	v_mad_i64_i32 v[116:117], s[0:1], v158, s95, v[138:139]
	global_store_dwordx4 v[116:117], v[112:115], off
	s_nop 1
	v_fmamk_f32 v112, v159, 0x3a000000, v239
	v_rsq_f32_e32 v112, v112
	s_nop 0
	v_mul_f32_e32 v114, v112, v112
	v_mul_f32_e32 v112, 0xbfb8aa3b, v112
	v_pk_mul_f32 v[108:109], v[108:109], v[112:113] op_sel_hi:[1,0]
	v_pk_mul_f32 v[104:105], v[104:105], v[114:115] op_sel_hi:[1,0]
	v_exp_f32_e32 v108, v108
	v_exp_f32_e32 v109, v109
	v_pk_mul_f32 v[96:97], v[96:97], v[112:113] op_sel_hi:[1,0]
	v_pk_mul_f32 v[98:99], v[98:99], v[112:113] op_sel_hi:[1,0]
	v_exp_f32_e32 v96, v96
	v_pk_add_f32 v[108:109], v[108:109], 1.0 op_sel_hi:[1,0]
	v_exp_f32_e32 v97, v97
	v_rcp_f32_e32 v108, v108
	v_rcp_f32_e32 v109, v109
	v_exp_f32_e32 v98, v98
	v_exp_f32_e32 v99, v99
	v_pk_add_f32 v[96:97], v[96:97], 1.0 op_sel_hi:[1,0]
	v_pk_mul_f32 v[104:105], v[104:105], v[108:109]
	v_pk_mul_f32 v[108:109], v[110:111], v[112:113] op_sel_hi:[1,0]
	v_rcp_f32_e32 v96, v96
	v_exp_f32_e32 v108, v108
	v_exp_f32_e32 v109, v109
	v_rcp_f32_e32 v97, v97
	v_pk_add_f32 v[98:99], v[98:99], 1.0 op_sel_hi:[1,0]
	v_pk_mul_f32 v[100:101], v[100:101], v[114:115] op_sel_hi:[1,0]
	v_pk_add_f32 v[108:109], v[108:109], 1.0 op_sel_hi:[1,0]
	v_rcp_f32_e32 v98, v98
	v_rcp_f32_e32 v108, v108
	v_rcp_f32_e32 v109, v109
	v_rcp_f32_e32 v99, v99
	v_pk_mul_f32 v[106:107], v[106:107], v[114:115] op_sel_hi:[1,0]
	v_pk_mul_f32 v[100:101], v[100:101], v[96:97]
	v_pk_mul_f32 v[96:97], v[102:103], v[114:115] op_sel_hi:[1,0]
	v_pk_mul_f32 v[106:107], v[106:107], v[108:109]
	v_pk_mul_f32 v[102:103], v[96:97], v[98:99]
	v_cvt_pk_bf16_f32 v96, v104, v105
	v_cvt_pk_bf16_f32 v97, v106, v107
	v_cvt_pk_bf16_f32 v98, v100, v101
	v_cvt_pk_bf16_f32 v99, v102, v103
	v_mad_i64_i32 v[100:101], s[0:1], v144, s95, v[138:139]
	global_store_dwordx4 v[100:101], v[96:99], off
	s_nop 1
	v_fmamk_f32 v96, v156, 0x3a000000, v239
	v_rsq_f32_e32 v97, v96
	s_nop 0
	v_mul_f32_e32 v98, 0xbfb8aa3b, v97
	v_pk_mul_f32 v[88:89], v[88:89], v[98:99] op_sel_hi:[1,0]
	v_pk_mul_f32 v[80:81], v[80:81], v[98:99] op_sel_hi:[1,0]
	v_exp_f32_e32 v88, v88
	v_exp_f32_e32 v89, v89
	v_pk_mul_f32 v[90:91], v[90:91], v[98:99] op_sel_hi:[1,0]
	v_exp_f32_e32 v80, v80
	v_exp_f32_e32 v81, v81
	v_pk_mul_f32 v[82:83], v[82:83], v[98:99] op_sel_hi:[1,0]
	v_exp_f32_e32 v90, v90
	v_exp_f32_e32 v91, v91
	v_exp_f32_e32 v82, v82
	v_exp_f32_e32 v83, v83
	v_pk_add_f32 v[88:89], v[88:89], 1.0 op_sel_hi:[1,0]
	v_pk_add_f32 v[80:81], v[80:81], 1.0 op_sel_hi:[1,0]
	v_rcp_f32_e32 v88, v88
	v_rcp_f32_e32 v89, v89
	v_pk_add_f32 v[90:91], v[90:91], 1.0 op_sel_hi:[1,0]
	v_rcp_f32_e32 v80, v80
	v_rcp_f32_e32 v81, v81
	v_pk_add_f32 v[82:83], v[82:83], 1.0 op_sel_hi:[1,0]
	v_rcp_f32_e32 v90, v90
	v_rcp_f32_e32 v91, v91
	v_rcp_f32_e32 v82, v82
	v_rcp_f32_e32 v83, v83
	v_mul_f32_e32 v96, v97, v97
	v_pk_mul_f32 v[92:93], v[92:93], v[96:97] op_sel_hi:[1,0]
	v_pk_mul_f32 v[84:85], v[84:85], v[96:97] op_sel_hi:[1,0]
	v_pk_mul_f32 v[88:89], v[92:93], v[88:89]
	v_pk_mul_f32 v[92:93], v[94:95], v[96:97] op_sel_hi:[1,0]
	v_pk_mul_f32 v[84:85], v[84:85], v[80:81]
	v_pk_mul_f32 v[80:81], v[86:87], v[96:97] op_sel_hi:[1,0]
	v_pk_mul_f32 v[90:91], v[92:93], v[90:91]
	v_pk_mul_f32 v[86:87], v[80:81], v[82:83]
	v_cvt_pk_bf16_f32 v80, v88, v89
	v_cvt_pk_bf16_f32 v81, v90, v91
	v_cvt_pk_bf16_f32 v82, v84, v85
	v_cvt_pk_bf16_f32 v83, v86, v87
	v_mad_i64_i32 v[84:85], s[0:1], v142, s95, v[138:139]
	global_store_dwordx4 v[84:85], v[80:83], off
	s_nop 1
	v_fmamk_f32 v80, v155, 0x3a000000, v239
	v_rsq_f32_e32 v81, v80
	s_nop 0
	v_mul_f32_e32 v82, 0xbfb8aa3b, v81
	v_pk_mul_f32 v[72:73], v[72:73], v[82:83] op_sel_hi:[1,0]
	v_pk_mul_f32 v[64:65], v[64:65], v[82:83] op_sel_hi:[1,0]
	v_exp_f32_e32 v72, v72
	v_exp_f32_e32 v73, v73
	v_pk_mul_f32 v[74:75], v[74:75], v[82:83] op_sel_hi:[1,0]
	v_exp_f32_e32 v64, v64
	v_exp_f32_e32 v65, v65
	v_pk_mul_f32 v[66:67], v[66:67], v[82:83] op_sel_hi:[1,0]
	v_exp_f32_e32 v74, v74
	v_exp_f32_e32 v75, v75
	v_exp_f32_e32 v66, v66
	v_exp_f32_e32 v67, v67
	v_pk_add_f32 v[72:73], v[72:73], 1.0 op_sel_hi:[1,0]
	v_pk_add_f32 v[64:65], v[64:65], 1.0 op_sel_hi:[1,0]
	v_rcp_f32_e32 v72, v72
	v_rcp_f32_e32 v73, v73
	v_pk_add_f32 v[74:75], v[74:75], 1.0 op_sel_hi:[1,0]
	v_rcp_f32_e32 v64, v64
	v_rcp_f32_e32 v65, v65
	v_pk_add_f32 v[66:67], v[66:67], 1.0 op_sel_hi:[1,0]
	v_rcp_f32_e32 v74, v74
	v_rcp_f32_e32 v75, v75
	v_rcp_f32_e32 v66, v66
	v_rcp_f32_e32 v67, v67
	v_mul_f32_e32 v80, v81, v81
	v_pk_mul_f32 v[76:77], v[76:77], v[80:81] op_sel_hi:[1,0]
	v_pk_mul_f32 v[68:69], v[68:69], v[80:81] op_sel_hi:[1,0]
	v_pk_mul_f32 v[72:73], v[76:77], v[72:73]
	v_pk_mul_f32 v[76:77], v[78:79], v[80:81] op_sel_hi:[1,0]
	v_pk_mul_f32 v[68:69], v[68:69], v[64:65]
	v_pk_mul_f32 v[64:65], v[70:71], v[80:81] op_sel_hi:[1,0]
	v_pk_mul_f32 v[74:75], v[76:77], v[74:75]
	v_pk_mul_f32 v[70:71], v[64:65], v[66:67]
	v_cvt_pk_bf16_f32 v64, v72, v73
	v_cvt_pk_bf16_f32 v65, v74, v75
	v_cvt_pk_bf16_f32 v66, v68, v69
	v_cvt_pk_bf16_f32 v67, v70, v71
	v_mad_i64_i32 v[68:69], s[0:1], v140, s95, v[138:139]
	global_store_dwordx4 v[68:69], v[64:67], off
	s_nop 1
	v_fmamk_f32 v64, v154, 0x3a000000, v239
	v_rsq_f32_e32 v65, v64
	s_nop 0
	v_mul_f32_e32 v66, 0xbfb8aa3b, v65
	v_pk_mul_f32 v[56:57], v[56:57], v[66:67] op_sel_hi:[1,0]
	v_pk_mul_f32 v[48:49], v[48:49], v[66:67] op_sel_hi:[1,0]
	v_exp_f32_e32 v56, v56
	v_exp_f32_e32 v57, v57
	v_pk_mul_f32 v[58:59], v[58:59], v[66:67] op_sel_hi:[1,0]
	v_exp_f32_e32 v48, v48
	v_exp_f32_e32 v49, v49
	v_pk_mul_f32 v[50:51], v[50:51], v[66:67] op_sel_hi:[1,0]
	v_exp_f32_e32 v58, v58
	v_exp_f32_e32 v59, v59
	v_exp_f32_e32 v50, v50
	v_exp_f32_e32 v51, v51
	v_pk_add_f32 v[56:57], v[56:57], 1.0 op_sel_hi:[1,0]
	v_pk_add_f32 v[48:49], v[48:49], 1.0 op_sel_hi:[1,0]
	v_rcp_f32_e32 v56, v56
	v_rcp_f32_e32 v57, v57
	v_pk_add_f32 v[58:59], v[58:59], 1.0 op_sel_hi:[1,0]
	v_rcp_f32_e32 v48, v48
	v_rcp_f32_e32 v49, v49
	v_pk_add_f32 v[50:51], v[50:51], 1.0 op_sel_hi:[1,0]
	v_rcp_f32_e32 v58, v58
	v_rcp_f32_e32 v59, v59
	v_rcp_f32_e32 v50, v50
	v_rcp_f32_e32 v51, v51
	v_mul_f32_e32 v64, v65, v65
	v_pk_mul_f32 v[60:61], v[60:61], v[64:65] op_sel_hi:[1,0]
	v_pk_mul_f32 v[52:53], v[52:53], v[64:65] op_sel_hi:[1,0]
	v_pk_mul_f32 v[56:57], v[60:61], v[56:57]
	v_pk_mul_f32 v[60:61], v[62:63], v[64:65] op_sel_hi:[1,0]
	v_pk_mul_f32 v[52:53], v[52:53], v[48:49]
	v_pk_mul_f32 v[48:49], v[54:55], v[64:65] op_sel_hi:[1,0]
	v_pk_mul_f32 v[58:59], v[60:61], v[58:59]
	v_pk_mul_f32 v[54:55], v[48:49], v[50:51]
	v_cvt_pk_bf16_f32 v48, v56, v57
	v_cvt_pk_bf16_f32 v49, v58, v59
	v_cvt_pk_bf16_f32 v50, v52, v53
	v_cvt_pk_bf16_f32 v51, v54, v55
	v_mad_i64_i32 v[52:53], s[0:1], v153, s95, v[138:139]
	global_store_dwordx4 v[52:53], v[48:51], off
	s_nop 1
	v_fmamk_f32 v48, v152, 0x3a000000, v239
	v_rsq_f32_e32 v49, v48
	s_nop 0
	v_mul_f32_e32 v50, 0xbfb8aa3b, v49
	v_pk_mul_f32 v[40:41], v[40:41], v[50:51] op_sel_hi:[1,0]
	v_pk_mul_f32 v[32:33], v[32:33], v[50:51] op_sel_hi:[1,0]
	v_exp_f32_e32 v40, v40
	v_exp_f32_e32 v41, v41
	v_pk_mul_f32 v[42:43], v[42:43], v[50:51] op_sel_hi:[1,0]
	v_exp_f32_e32 v32, v32
	v_exp_f32_e32 v33, v33
	v_pk_mul_f32 v[34:35], v[34:35], v[50:51] op_sel_hi:[1,0]
	v_exp_f32_e32 v42, v42
	v_exp_f32_e32 v43, v43
	v_exp_f32_e32 v34, v34
	v_exp_f32_e32 v35, v35
	v_pk_add_f32 v[40:41], v[40:41], 1.0 op_sel_hi:[1,0]
	v_pk_add_f32 v[32:33], v[32:33], 1.0 op_sel_hi:[1,0]
	v_rcp_f32_e32 v40, v40
	v_rcp_f32_e32 v41, v41
	v_pk_add_f32 v[42:43], v[42:43], 1.0 op_sel_hi:[1,0]
	v_rcp_f32_e32 v32, v32
	v_rcp_f32_e32 v33, v33
	v_pk_add_f32 v[34:35], v[34:35], 1.0 op_sel_hi:[1,0]
	v_rcp_f32_e32 v42, v42
	v_rcp_f32_e32 v43, v43
	v_rcp_f32_e32 v34, v34
	v_rcp_f32_e32 v35, v35
	v_mul_f32_e32 v48, v49, v49
	v_pk_mul_f32 v[44:45], v[44:45], v[48:49] op_sel_hi:[1,0]
	v_pk_mul_f32 v[36:37], v[36:37], v[48:49] op_sel_hi:[1,0]
	v_pk_mul_f32 v[40:41], v[44:45], v[40:41]
	v_pk_mul_f32 v[44:45], v[46:47], v[48:49] op_sel_hi:[1,0]
	v_pk_mul_f32 v[36:37], v[36:37], v[32:33]
	v_pk_mul_f32 v[32:33], v[38:39], v[48:49] op_sel_hi:[1,0]
	v_pk_mul_f32 v[42:43], v[44:45], v[42:43]
	v_pk_mul_f32 v[38:39], v[32:33], v[34:35]
	v_cvt_pk_bf16_f32 v32, v40, v41
	v_cvt_pk_bf16_f32 v33, v42, v43
	v_cvt_pk_bf16_f32 v34, v36, v37
	v_cvt_pk_bf16_f32 v35, v38, v39
	v_mad_i64_i32 v[36:37], s[0:1], v151, s95, v[138:139]
	global_store_dwordx4 v[36:37], v[32:35], off
	s_nop 1
	v_fmamk_f32 v32, v150, 0x3a000000, v239
	v_rsq_f32_e32 v33, v32
	s_nop 0
	v_mul_f32_e32 v34, 0xbfb8aa3b, v33
	v_pk_mul_f32 v[24:25], v[24:25], v[34:35] op_sel_hi:[1,0]
	v_pk_mul_f32 v[16:17], v[16:17], v[34:35] op_sel_hi:[1,0]
	v_exp_f32_e32 v24, v24
	v_exp_f32_e32 v25, v25
	v_pk_mul_f32 v[26:27], v[26:27], v[34:35] op_sel_hi:[1,0]
	v_exp_f32_e32 v16, v16
	v_exp_f32_e32 v17, v17
	v_pk_mul_f32 v[18:19], v[18:19], v[34:35] op_sel_hi:[1,0]
	v_exp_f32_e32 v26, v26
	v_exp_f32_e32 v27, v27
	v_exp_f32_e32 v18, v18
	v_exp_f32_e32 v19, v19
	v_pk_add_f32 v[24:25], v[24:25], 1.0 op_sel_hi:[1,0]
	v_pk_add_f32 v[16:17], v[16:17], 1.0 op_sel_hi:[1,0]
	v_rcp_f32_e32 v24, v24
	v_rcp_f32_e32 v25, v25
	v_pk_add_f32 v[26:27], v[26:27], 1.0 op_sel_hi:[1,0]
	v_rcp_f32_e32 v16, v16
	v_rcp_f32_e32 v17, v17
	v_pk_add_f32 v[18:19], v[18:19], 1.0 op_sel_hi:[1,0]
	v_rcp_f32_e32 v26, v26
	v_rcp_f32_e32 v27, v27
	v_rcp_f32_e32 v18, v18
	v_rcp_f32_e32 v19, v19
	v_mul_f32_e32 v32, v33, v33
	v_pk_mul_f32 v[28:29], v[28:29], v[32:33] op_sel_hi:[1,0]
	v_pk_mul_f32 v[20:21], v[20:21], v[32:33] op_sel_hi:[1,0]
	v_pk_mul_f32 v[24:25], v[28:29], v[24:25]
	v_pk_mul_f32 v[28:29], v[30:31], v[32:33] op_sel_hi:[1,0]
	v_pk_mul_f32 v[20:21], v[20:21], v[16:17]
	v_pk_mul_f32 v[16:17], v[22:23], v[32:33] op_sel_hi:[1,0]
	v_pk_mul_f32 v[26:27], v[28:29], v[26:27]
	v_pk_mul_f32 v[22:23], v[16:17], v[18:19]
	v_cvt_pk_bf16_f32 v16, v24, v25
	v_cvt_pk_bf16_f32 v17, v26, v27
	v_cvt_pk_bf16_f32 v18, v20, v21
	v_cvt_pk_bf16_f32 v19, v22, v23
	v_mad_i64_i32 v[20:21], s[0:1], v145, s95, v[138:139]
	global_store_dwordx4 v[20:21], v[16:19], off
	s_nop 1
	v_fmamk_f32 v16, v143, 0x3a000000, v239
	v_rsq_f32_e32 v17, v16
	s_nop 0
	v_mul_f32_e32 v18, 0xbfb8aa3b, v17
	v_pk_mul_f32 v[8:9], v[8:9], v[18:19] op_sel_hi:[1,0]
	v_pk_mul_f32 v[0:1], v[0:1], v[18:19] op_sel_hi:[1,0]
	v_exp_f32_e32 v8, v8
	v_exp_f32_e32 v9, v9
	v_pk_mul_f32 v[10:11], v[10:11], v[18:19] op_sel_hi:[1,0]
	v_exp_f32_e32 v0, v0
	v_exp_f32_e32 v1, v1
	v_pk_mul_f32 v[2:3], v[2:3], v[18:19] op_sel_hi:[1,0]
	v_exp_f32_e32 v10, v10
	v_exp_f32_e32 v11, v11
	v_exp_f32_e32 v2, v2
	v_exp_f32_e32 v3, v3
	v_pk_add_f32 v[8:9], v[8:9], 1.0 op_sel_hi:[1,0]
	v_pk_add_f32 v[0:1], v[0:1], 1.0 op_sel_hi:[1,0]
	v_rcp_f32_e32 v8, v8
	v_rcp_f32_e32 v9, v9
	v_pk_add_f32 v[10:11], v[10:11], 1.0 op_sel_hi:[1,0]
	v_rcp_f32_e32 v0, v0
	v_rcp_f32_e32 v1, v1
	v_pk_add_f32 v[2:3], v[2:3], 1.0 op_sel_hi:[1,0]
	v_rcp_f32_e32 v10, v10
	v_rcp_f32_e32 v11, v11
	v_rcp_f32_e32 v2, v2
	v_rcp_f32_e32 v3, v3
	v_mul_f32_e32 v16, v17, v17
	v_pk_mul_f32 v[12:13], v[12:13], v[16:17] op_sel_hi:[1,0]
	v_pk_mul_f32 v[4:5], v[4:5], v[16:17] op_sel_hi:[1,0]
	v_pk_mul_f32 v[8:9], v[12:13], v[8:9]
	v_pk_mul_f32 v[12:13], v[14:15], v[16:17] op_sel_hi:[1,0]
	v_pk_mul_f32 v[4:5], v[4:5], v[0:1]
	v_pk_mul_f32 v[0:1], v[6:7], v[16:17] op_sel_hi:[1,0]
	v_pk_mul_f32 v[10:11], v[12:13], v[10:11]
	v_pk_mul_f32 v[6:7], v[0:1], v[2:3]
	v_cvt_pk_bf16_f32 v0, v8, v9
	v_cvt_pk_bf16_f32 v1, v10, v11
	v_cvt_pk_bf16_f32 v2, v4, v5
	v_cvt_pk_bf16_f32 v3, v6, v7
	v_mad_i64_i32 v[4:5], s[0:1], v141, s95, v[138:139]
	global_store_dwordx4 v[4:5], v[0:3], off
	s_cbranch_vccnz .LBB0_524
	s_andn2_b64 vcc, exec, s[8:9]
	s_cbranch_vccnz .LBB0_523
	s_barrier
	s_branch .LBB0_523
